# P0 p->bf16 conversion: the 8 per-thread float4 loads issued together (unrolled) instead of one load+wait per iteration
# speedup vs baseline: 1.0257x; 1.0028x over previous
; __device__ __forceinline__ unsigned cvt_pk_bf16(float lo, float hi) { unsigned r; asm volatile("v_cvt_pk_bf16_f32 %0, %1, %2" : "=v"(r) : "v"(lo), "v"(hi)); return r; }
; __device__ void phase0(const Params& p, LAS unsigned char* lds, const int WID) {
;     ...
;     { const float* pin = p.in[1]; bf16_t* pb = (bf16_t*)(ws + WS_PB);
;       for (int i = bx * 512 + tid; i < MTOK * PLE / 4; i += G * 512) { const f32x4 v = __builtin_nontemporal_load((const f32x4*)(pin + (size_t)i * 4)); u32x2 w; w.x = cvt_pk_bf16(v[0], v[1]); w.y = cvt_pk_bf16(v[2], v[3]); *(u32x2*)(pb + (size_t)i * 4) = w; } }
.LBB0_7:
	s_and_b32 s92, s40, 0xffffffc0
	s_waitcnt lgkmcnt(0)
	s_lshl_b32 s60, s2, 9
	v_add_u32_e32 v20, s92, v42
	v_add_u32_e32 v2, s60, v20
	s_mov_b32 s0, 0x100000
	s_lshl_b32 s54, s96, 9
	v_cmp_gt_i32_e32 vcc, s0, v2
	s_and_saveexec_b64 s[0:1], vcc
	s_cbranch_execz .LBB0_10
	v_ashrrev_i32_e32 v3, 31, v2
	v_mov_b32_e32 v4, s58
	v_mov_b32_e32 v5, s59
	s_ashr_i32 s55, s54, 31
	v_lshl_add_u64 v[6:7], v[2:3], 3, s[94:95]
	s_mov_b64 s[8:9], 0x1d600000
	v_lshl_add_u64 v[4:5], v[2:3], 4, v[4:5]
	s_lshl_b64 s[6:7], s[54:55], 4
	v_lshl_add_u64 v[6:7], v[6:7], 0, s[8:9]
	s_lshl_b64 s[8:9], s[54:55], 3
	s_mov_b64 s[10:11], 0
	s_mov_b32 s12, 0xfffff
	s_cmp_lg_u32 s96, 0x100
	s_cbranch_scc1 .LBB0_9
	v_lshl_add_u64 v[46:47], v[4:5], 0, s[6:7]
	v_lshl_add_u64 v[48:49], v[46:47], 0, s[6:7]
	v_lshl_add_u64 v[50:51], v[48:49], 0, s[6:7]
	v_lshl_add_u64 v[52:53], v[50:51], 0, s[6:7]
	v_lshl_add_u64 v[54:55], v[52:53], 0, s[6:7]
	v_lshl_add_u64 v[56:57], v[54:55], 0, s[6:7]
	v_lshl_add_u64 v[58:59], v[56:57], 0, s[6:7]
	global_load_dwordx4 v[8:11], v[4:5], off nt
	global_load_dwordx4 v[74:77], v[46:47], off nt
	global_load_dwordx4 v[78:81], v[48:49], off nt
	global_load_dwordx4 v[82:85], v[50:51], off nt
	global_load_dwordx4 v[86:89], v[52:53], off nt
	global_load_dwordx4 v[90:93], v[54:55], off nt
	global_load_dwordx4 v[94:97], v[56:57], off nt
	global_load_dwordx4 v[98:101], v[58:59], off nt
	v_lshl_add_u64 v[60:61], v[6:7], 0, s[8:9]
	v_lshl_add_u64 v[62:63], v[60:61], 0, s[8:9]
	v_lshl_add_u64 v[64:65], v[62:63], 0, s[8:9]
	v_lshl_add_u64 v[66:67], v[64:65], 0, s[8:9]
	v_lshl_add_u64 v[68:69], v[66:67], 0, s[8:9]
	v_lshl_add_u64 v[70:71], v[68:69], 0, s[8:9]
	v_lshl_add_u64 v[72:73], v[70:71], 0, s[8:9]
	s_waitcnt vmcnt(7)
	v_cvt_pk_bf16_f32 v8, v8, v9
	v_cvt_pk_bf16_f32 v9, v10, v11
	global_store_dwordx2 v[6:7], v[8:9], off
	s_waitcnt vmcnt(7)
	v_cvt_pk_bf16_f32 v74, v74, v75
	v_cvt_pk_bf16_f32 v75, v76, v77
	global_store_dwordx2 v[60:61], v[74:75], off
	s_waitcnt vmcnt(7)
	v_cvt_pk_bf16_f32 v78, v78, v79
	v_cvt_pk_bf16_f32 v79, v80, v81
	global_store_dwordx2 v[62:63], v[78:79], off
	s_waitcnt vmcnt(7)
	v_cvt_pk_bf16_f32 v82, v82, v83
	v_cvt_pk_bf16_f32 v83, v84, v85
	global_store_dwordx2 v[64:65], v[82:83], off
	s_waitcnt vmcnt(7)
	v_cvt_pk_bf16_f32 v86, v86, v87
	v_cvt_pk_bf16_f32 v87, v88, v89
	global_store_dwordx2 v[66:67], v[86:87], off
	s_waitcnt vmcnt(7)
	v_cvt_pk_bf16_f32 v90, v90, v91
	v_cvt_pk_bf16_f32 v91, v92, v93
	global_store_dwordx2 v[68:69], v[90:91], off
	s_waitcnt vmcnt(7)
	v_cvt_pk_bf16_f32 v94, v94, v95
	v_cvt_pk_bf16_f32 v95, v96, v97
	global_store_dwordx2 v[70:71], v[94:95], off
	s_waitcnt vmcnt(7)
	v_cvt_pk_bf16_f32 v98, v98, v99
	v_cvt_pk_bf16_f32 v99, v100, v101
	global_store_dwordx2 v[72:73], v[98:99], off
	s_branch .LBB0_10
